# P2(c) unit prologue: CR, VV and gate-weight loads issued together (one round trip instead of three)
# speedup vs baseline: 1.0082x; 1.0082x over previous
.LBB0_240:
	s_lshl_b32 s44, s47, 4
	s_andn2_b32 s44, s44, 63
	s_and_saveexec_b64 s[42:43], s[8:9]
	s_cbranch_execz .LBB0_242
	v_add_u32_e32 v100, s44, v62
	v_ashrrev_i32_e32 v101, 31, v100
	v_lshlrev_b64 v[100:101], 7, v[100:101]
	v_lshl_add_u64 v[100:101], v[40:41], 0, v[100:101]
	global_load_dwordx4 v[102:105], v[100:101], off offset:32
.LBB0_242:
	s_or_b64 exec, exec, s[42:43]
	s_and_b32 s48, s47, 3
	v_add_u32_e32 v88, s44, v27
	v_mov_b64_e32 v[96:97], s[0:1]
	v_mad_i64_i32 v[88:89], s[42:43], v88, s35, v[96:97]
	s_mul_i32 s14, s48, 0x180
	v_lshl_add_u64 v[88:89], v[88:89], 0, s[14:15]
	v_add_u32_e32 v90, s44, v60
	v_lshl_add_u64 v[88:89], v[18:19], 1, v[88:89]
	v_mad_i64_i32 v[90:91], s[42:43], v90, s35, v[96:97]
	v_add_co_u32_e32 v88, vcc, 0x2000, v88
	v_lshl_add_u64 v[90:91], v[90:91], 0, s[14:15]
	s_nop 0
	v_addc_co_u32_e32 v89, vcc, 0, v89, vcc
	v_lshl_add_u64 v[90:91], v[20:21], 1, v[90:91]
	v_add_co_u32_e32 v92, vcc, 0x2000, v90
	v_add_u32_e32 v98, s44, v61
	s_nop 0
	v_addc_co_u32_e32 v93, vcc, 0, v91, vcc
	global_load_dwordx4 v[88:91], v[88:89], off offset:3584
	s_nop 0
	global_load_dwordx4 v[92:95], v[92:93], off offset:3584
	v_mad_i64_i32 v[96:97], s[42:43], v98, s35, v[96:97]
	v_lshl_add_u64 v[96:97], v[96:97], 0, s[14:15]
	v_lshl_add_u64 v[96:97], v[22:23], 1, v[96:97]
	v_add_co_u32_e32 v96, vcc, 0x2000, v96
	s_nop 1
	v_addc_co_u32_e32 v97, vcc, 0, v97, vcc
	global_load_dwordx4 v[96:99], v[96:97], off offset:3584
	s_and_saveexec_b64 s[44:45], s[4:5]
	s_cbranch_execz .Lp2_nog
	s_mul_i32 s14, s48, 0x60
	v_add_u32_e32 v2, s14, v24
	v_ashrrev_i32_e32 v3, 31, v2
	v_lshlrev_b64 v[42:43], 2, v[2:3]
	v_lshl_add_u64 v[44:45], s[10:11], 0, v[42:43]
	v_add_co_u32_e32 v10, vcc, 0x1000, v44
	global_load_dword v4, v[44:45], off
	global_load_dword v6, v[44:45], off offset:1536
	global_load_dword v2, v[44:45], off offset:3072
	v_addc_co_u32_e32 v11, vcc, 0, v45, vcc
	global_load_dword v8, v[10:11], off offset:512
	global_load_dword v5, v[10:11], off offset:2048
	global_load_dword v7, v[10:11], off offset:3584
	v_add_co_u32_e32 v10, vcc, s22, v44
	s_movk_i32 s14, 0x4000
	s_nop 0
	v_addc_co_u32_e32 v11, vcc, 0, v45, vcc
	global_load_dword v3, v[10:11], off offset:1024
	global_load_dword v9, v[10:11], off offset:2560
	v_add_co_u32_e32 v10, vcc, 0x3000, v44
	v_lshl_add_u64 v[42:43], s[24:25], 0, v[42:43]
	s_nop 0
	v_addc_co_u32_e32 v11, vcc, 0, v45, vcc
	v_add_co_u32_e32 v46, vcc, s14, v44
	global_load_dword v12, v[10:11], off
	global_load_dword v14, v[10:11], off offset:1536
	s_nop 0
	global_load_dword v10, v[10:11], off offset:3072
	v_addc_co_u32_e32 v47, vcc, 0, v45, vcc
	v_add_co_u32_e32 v44, vcc, 0x5000, v44
	global_load_dword v16, v[46:47], off offset:512
	global_load_dword v13, v[46:47], off offset:2048
	global_load_dword v15, v[46:47], off offset:3584
	v_addc_co_u32_e32 v45, vcc, 0, v45, vcc
	global_load_dword v11, v[44:45], off offset:1024
	global_load_dword v17, v[44:45], off offset:2560
	global_load_dword v42, v[42:43], off
	s_or_b64 exec, exec, s[44:45]
	s_waitcnt vmcnt(17)
	s_branch .Lp2_w
.Lp2_nog:
	s_or_b64 exec, exec, s[44:45]
	s_waitcnt vmcnt(0)
.Lp2_w:
	ds_write_b128 v68, v[88:91] offset:21504
	ds_write_b128 v69, v[92:95] offset:21504
	ds_write_b128 v70, v[96:99] offset:21504
	s_and_saveexec_b64 s[42:43], s[8:9]
	ds_write_b128 v63, v[102:105]
	s_or_b64 exec, exec, s[42:43]
	s_waitcnt lgkmcnt(0)
	s_barrier
	s_and_saveexec_b64 s[44:45], s[4:5]
	s_cbranch_execz .LBB0_244
	s_mov_b32 s14, 0x3d800000
	ds_read_b128 v[44:47], v65
	ds_read_b128 v[48:51], v65 offset:16
	ds_read_b128 v[52:55], v65 offset:32
	ds_read_b128 v[56:59], v65 offset:48
	s_waitcnt lgkmcnt(3)
	v_mov_b32_e32 v72, v44
	s_waitcnt lgkmcnt(2)
	v_mov_b32_e32 v73, v48
	v_mov_b32_e32 v48, v45
	s_waitcnt vmcnt(11)
	v_pk_mul_f32 v[44:45], v[6:7], v[48:49]
	s_nop 0
	v_pk_fma_f32 v[44:45], v[4:5], v[72:73], v[44:45]
	v_mov_b32_e32 v48, v46
	v_mov_b32_e32 v49, v50
	v_mov_b32_e32 v50, v47
	s_waitcnt vmcnt(10)
	v_pk_fma_f32 v[44:45], v[2:3], v[48:49], v[44:45]
	s_waitcnt vmcnt(9)
	v_pk_fma_f32 v[44:45], v[8:9], v[50:51], v[44:45]
	s_waitcnt vmcnt(0)
	v_add_f32_e32 v43, v42, v44
	v_add_f32_e32 v43, v43, v45
	s_waitcnt lgkmcnt(0)
	v_mov_b32_e32 v45, v56
	v_mov_b32_e32 v56, v53
	v_mov_b32_e32 v44, v52
	v_pk_mul_f32 v[46:47], v[14:15], v[56:57]
	s_nop 0
	v_pk_fma_f32 v[44:45], v[12:13], v[44:45], v[46:47]
	v_mov_b32_e32 v46, v54
	v_mov_b32_e32 v47, v58
	v_pk_fma_f32 v[44:45], v[10:11], v[46:47], v[44:45]
	v_mov_b32_e32 v58, v55
	v_pk_fma_f32 v[44:45], v[16:17], v[58:59], v[44:45]
	s_nop 0
	v_add_f32_e32 v43, v43, v44
	v_add_f32_e32 v43, v43, v45
	v_min_f32_e32 v44, 0, v43
	v_mul_f32_e64 v43, |v43|, s82
	v_exp_f32_e32 v43, v43
	s_nop 0
	v_add_f32_e32 v43, 1.0, v43
	v_cmp_gt_f32_e32 vcc, s2, v43
	s_nop 1
	v_cndmask_b32_e64 v45, 0, 32, vcc
	v_ldexp_f32 v43, v43, v45
	v_log_f32_e32 v43, v43
	s_nop 0
	v_mul_f32_e32 v45, 0x3f317217, v43
	v_fma_f32 v45, v43, s85, -v45
	v_fmac_f32_e32 v45, 0x3377d1cf, v43
	v_fmac_f32_e32 v45, 0x3f317217, v43
	v_cmp_lt_f32_e64 s[42:43], |v43|, s83
	s_nop 1
	v_cndmask_b32_e64 v43, v43, v45, s[42:43]
	v_cndmask_b32_e32 v45, 0, v200, vcc
	v_sub_f32_e32 v43, v43, v45
	v_sub_f32_e32 v43, v44, v43
	ds_read_b128 v[44:47], v65 offset:64
	ds_read_b128 v[48:51], v65 offset:80
	v_fma_f32 v72, v43, s14, 0
	s_waitcnt lgkmcnt(1)
	v_mov_b32_e32 v52, v44
	s_waitcnt lgkmcnt(0)
	v_mov_b32_e32 v53, v48
	v_mov_b32_e32 v48, v45
	v_pk_mul_f32 v[44:45], v[6:7], v[48:49]
	v_mov_b32_e32 v48, v46
	v_pk_fma_f32 v[44:45], v[4:5], v[52:53], v[44:45]
	v_mov_b32_e32 v49, v50
	v_pk_fma_f32 v[44:45], v[2:3], v[48:49], v[44:45]
	v_mov_b32_e32 v50, v47
	v_pk_fma_f32 v[44:45], v[8:9], v[50:51], v[44:45]
	s_nop 0
	v_add_f32_e32 v43, v42, v44
	v_add_f32_e32 v43, v43, v45
	ds_read_b128 v[44:47], v65 offset:96
	ds_read_b128 v[48:51], v65 offset:112
	s_waitcnt lgkmcnt(1)
	v_mov_b32_e32 v52, v44
	s_waitcnt lgkmcnt(0)
	v_mov_b32_e32 v53, v48
	v_mov_b32_e32 v48, v45
	v_pk_mul_f32 v[44:45], v[14:15], v[48:49]
	v_mov_b32_e32 v48, v46
	v_pk_fma_f32 v[44:45], v[12:13], v[52:53], v[44:45]
	v_mov_b32_e32 v49, v50
	v_pk_fma_f32 v[44:45], v[10:11], v[48:49], v[44:45]
	v_mov_b32_e32 v50, v47
	v_pk_fma_f32 v[44:45], v[16:17], v[50:51], v[44:45]
	s_nop 0
	v_add_f32_e32 v43, v43, v44
	v_add_f32_e32 v43, v43, v45
	v_min_f32_e32 v44, 0, v43
	v_mul_f32_e64 v43, |v43|, s82
	v_exp_f32_e32 v43, v43
	s_nop 0
	v_add_f32_e32 v43, 1.0, v43
	v_cmp_gt_f32_e32 vcc, s2, v43
	s_nop 1
	v_cndmask_b32_e64 v45, 0, 32, vcc
	v_ldexp_f32 v43, v43, v45
	v_log_f32_e32 v43, v43
	s_nop 0
	v_mul_f32_e32 v45, 0x3f317217, v43
	v_fma_f32 v45, v43, s85, -v45
	v_fmac_f32_e32 v45, 0x3377d1cf, v43
	v_fmac_f32_e32 v45, 0x3f317217, v43
	v_cmp_lt_f32_e64 s[42:43], |v43|, s83
	s_nop 1
	v_cndmask_b32_e64 v43, v43, v45, s[42:43]
	v_cndmask_b32_e32 v45, 0, v200, vcc
	v_sub_f32_e32 v43, v43, v45
	v_sub_f32_e32 v43, v44, v43
	ds_read_b128 v[44:47], v65 offset:128
	ds_read_b128 v[48:51], v65 offset:144
	v_fmamk_f32 v73, v43, 0x3d800000, v72
	s_waitcnt lgkmcnt(1)
	v_mov_b32_e32 v52, v44
	s_waitcnt lgkmcnt(0)
	v_mov_b32_e32 v53, v48
	v_mov_b32_e32 v48, v45
	v_pk_mul_f32 v[44:45], v[6:7], v[48:49]
	v_mov_b32_e32 v48, v46
	v_pk_fma_f32 v[44:45], v[4:5], v[52:53], v[44:45]
	v_mov_b32_e32 v49, v50
	v_pk_fma_f32 v[44:45], v[2:3], v[48:49], v[44:45]
	v_mov_b32_e32 v50, v47
	v_pk_fma_f32 v[44:45], v[8:9], v[50:51], v[44:45]
	s_nop 0
	v_add_f32_e32 v43, v42, v44
	v_add_f32_e32 v43, v43, v45
	ds_read_b128 v[44:47], v65 offset:160
	ds_read_b128 v[48:51], v65 offset:176
	s_waitcnt lgkmcnt(1)
	v_mov_b32_e32 v52, v44
	s_waitcnt lgkmcnt(0)
	v_mov_b32_e32 v53, v48
	v_mov_b32_e32 v48, v45
	v_pk_mul_f32 v[44:45], v[14:15], v[48:49]
	v_mov_b32_e32 v48, v46
	v_pk_fma_f32 v[44:45], v[12:13], v[52:53], v[44:45]
	v_mov_b32_e32 v49, v50
	v_pk_fma_f32 v[44:45], v[10:11], v[48:49], v[44:45]
	v_mov_b32_e32 v50, v47
	v_pk_fma_f32 v[44:45], v[16:17], v[50:51], v[44:45]
	s_nop 0
	v_add_f32_e32 v43, v43, v44
	v_add_f32_e32 v43, v43, v45
	v_min_f32_e32 v44, 0, v43
	v_mul_f32_e64 v43, |v43|, s82
	v_exp_f32_e32 v43, v43
	s_nop 0
	v_add_f32_e32 v43, 1.0, v43
	v_cmp_gt_f32_e32 vcc, s2, v43
	s_nop 1
	v_cndmask_b32_e64 v45, 0, 32, vcc
	v_ldexp_f32 v43, v43, v45
	v_log_f32_e32 v43, v43
	s_nop 0
	v_mul_f32_e32 v45, 0x3f317217, v43
	v_fma_f32 v45, v43, s85, -v45
	v_fmac_f32_e32 v45, 0x3377d1cf, v43
	v_fmac_f32_e32 v45, 0x3f317217, v43
	v_cmp_lt_f32_e64 s[42:43], |v43|, s83
	s_nop 1
	v_cndmask_b32_e64 v43, v43, v45, s[42:43]
	v_cndmask_b32_e32 v45, 0, v200, vcc
	v_sub_f32_e32 v43, v43, v45
	v_sub_f32_e32 v43, v44, v43
	ds_read_b128 v[44:47], v65 offset:192
	ds_read_b128 v[48:51], v65 offset:208
	v_fmamk_f32 v74, v43, 0x3d800000, v73
	s_waitcnt lgkmcnt(1)
	v_mov_b32_e32 v52, v44
	s_waitcnt lgkmcnt(0)
	v_mov_b32_e32 v53, v48
	v_mov_b32_e32 v48, v45
	v_pk_mul_f32 v[44:45], v[6:7], v[48:49]
	v_mov_b32_e32 v48, v46
	v_pk_fma_f32 v[44:45], v[4:5], v[52:53], v[44:45]
	v_mov_b32_e32 v49, v50
	v_pk_fma_f32 v[44:45], v[2:3], v[48:49], v[44:45]
	v_mov_b32_e32 v50, v47
	v_pk_fma_f32 v[44:45], v[8:9], v[50:51], v[44:45]
	s_nop 0
	v_add_f32_e32 v43, v42, v44
	v_add_f32_e32 v43, v43, v45
	ds_read_b128 v[44:47], v65 offset:224
	ds_read_b128 v[48:51], v65 offset:240
	s_waitcnt lgkmcnt(1)
	v_mov_b32_e32 v52, v44
	s_waitcnt lgkmcnt(0)
	v_mov_b32_e32 v53, v48
	v_mov_b32_e32 v48, v45
	v_pk_mul_f32 v[44:45], v[14:15], v[48:49]
	v_mov_b32_e32 v48, v46
	v_pk_fma_f32 v[44:45], v[12:13], v[52:53], v[44:45]
	v_mov_b32_e32 v49, v50
	v_pk_fma_f32 v[44:45], v[10:11], v[48:49], v[44:45]
	v_mov_b32_e32 v50, v47
	v_pk_fma_f32 v[44:45], v[16:17], v[50:51], v[44:45]
	s_nop 0
	v_add_f32_e32 v43, v43, v44
	v_add_f32_e32 v43, v43, v45
	v_min_f32_e32 v44, 0, v43
	v_mul_f32_e64 v43, |v43|, s82
	v_exp_f32_e32 v43, v43
	s_nop 0
	v_add_f32_e32 v43, 1.0, v43
	v_cmp_gt_f32_e32 vcc, s2, v43
	s_nop 1
	v_cndmask_b32_e64 v45, 0, 32, vcc
	v_ldexp_f32 v43, v43, v45
	v_log_f32_e32 v43, v43
	s_nop 0
	v_mul_f32_e32 v45, 0x3f317217, v43
	v_fma_f32 v45, v43, s85, -v45
	v_fmac_f32_e32 v45, 0x3377d1cf, v43
	v_fmac_f32_e32 v45, 0x3f317217, v43
	v_cmp_lt_f32_e64 s[42:43], |v43|, s83
	s_nop 1
	v_cndmask_b32_e64 v43, v43, v45, s[42:43]
	v_cndmask_b32_e32 v45, 0, v200, vcc
	v_sub_f32_e32 v43, v43, v45
	v_sub_f32_e32 v43, v44, v43
	ds_read_b128 v[44:47], v65 offset:256
	ds_read_b128 v[48:51], v65 offset:272
	v_fmamk_f32 v75, v43, 0x3d800000, v74
	s_waitcnt lgkmcnt(1)
	v_mov_b32_e32 v52, v44
	s_waitcnt lgkmcnt(0)
	v_mov_b32_e32 v53, v48
	v_mov_b32_e32 v48, v45
	v_pk_mul_f32 v[44:45], v[6:7], v[48:49]
	v_mov_b32_e32 v48, v46
	v_pk_fma_f32 v[44:45], v[4:5], v[52:53], v[44:45]
	v_mov_b32_e32 v49, v50
	v_pk_fma_f32 v[44:45], v[2:3], v[48:49], v[44:45]
	v_mov_b32_e32 v50, v47
	v_pk_fma_f32 v[44:45], v[8:9], v[50:51], v[44:45]
	s_nop 0
	v_add_f32_e32 v43, v42, v44
	v_add_f32_e32 v43, v43, v45
	ds_read_b128 v[44:47], v65 offset:288
	ds_read_b128 v[48:51], v65 offset:304
	s_waitcnt lgkmcnt(1)
	v_mov_b32_e32 v52, v44
	s_waitcnt lgkmcnt(0)
	v_mov_b32_e32 v53, v48
	v_mov_b32_e32 v48, v45
	v_pk_mul_f32 v[44:45], v[14:15], v[48:49]
	v_mov_b32_e32 v48, v46
	v_pk_fma_f32 v[44:45], v[12:13], v[52:53], v[44:45]
	v_mov_b32_e32 v49, v50
	v_pk_fma_f32 v[44:45], v[10:11], v[48:49], v[44:45]
	v_mov_b32_e32 v50, v47
	v_pk_fma_f32 v[44:45], v[16:17], v[50:51], v[44:45]
	s_nop 0
	v_add_f32_e32 v43, v43, v44
	v_add_f32_e32 v43, v43, v45
	v_min_f32_e32 v44, 0, v43
	v_mul_f32_e64 v43, |v43|, s82
	v_exp_f32_e32 v43, v43
	s_nop 0
	v_add_f32_e32 v43, 1.0, v43
	v_cmp_gt_f32_e32 vcc, s2, v43
	s_nop 1
	v_cndmask_b32_e64 v45, 0, 32, vcc
	v_ldexp_f32 v43, v43, v45
	v_log_f32_e32 v43, v43
	s_nop 0
	v_mul_f32_e32 v45, 0x3f317217, v43
	v_fma_f32 v45, v43, s85, -v45
	v_fmac_f32_e32 v45, 0x3377d1cf, v43
	v_fmac_f32_e32 v45, 0x3f317217, v43
	v_cmp_lt_f32_e64 s[42:43], |v43|, s83
	s_nop 1
	v_cndmask_b32_e64 v43, v43, v45, s[42:43]
	v_cndmask_b32_e32 v45, 0, v200, vcc
	v_sub_f32_e32 v43, v43, v45
	v_sub_f32_e32 v43, v44, v43
	ds_read_b128 v[44:47], v65 offset:320
	ds_read_b128 v[48:51], v65 offset:336
	v_fmamk_f32 v76, v43, 0x3d800000, v75
	s_waitcnt lgkmcnt(1)
	v_mov_b32_e32 v52, v44
	s_waitcnt lgkmcnt(0)
	v_mov_b32_e32 v53, v48
	v_mov_b32_e32 v48, v45
	v_pk_mul_f32 v[44:45], v[6:7], v[48:49]
	v_mov_b32_e32 v48, v46
	v_pk_fma_f32 v[44:45], v[4:5], v[52:53], v[44:45]
	v_mov_b32_e32 v49, v50
	v_pk_fma_f32 v[44:45], v[2:3], v[48:49], v[44:45]
	v_mov_b32_e32 v50, v47
	v_pk_fma_f32 v[44:45], v[8:9], v[50:51], v[44:45]
	s_nop 0
	v_add_f32_e32 v43, v42, v44
	v_add_f32_e32 v43, v43, v45
	ds_read_b128 v[44:47], v65 offset:352
	ds_read_b128 v[48:51], v65 offset:368
	s_waitcnt lgkmcnt(1)
	v_mov_b32_e32 v52, v44
	s_waitcnt lgkmcnt(0)
	v_mov_b32_e32 v53, v48
	v_mov_b32_e32 v48, v45
	v_pk_mul_f32 v[44:45], v[14:15], v[48:49]
	v_mov_b32_e32 v48, v46
	v_pk_fma_f32 v[44:45], v[12:13], v[52:53], v[44:45]
	v_mov_b32_e32 v49, v50
	v_pk_fma_f32 v[44:45], v[10:11], v[48:49], v[44:45]
	v_mov_b32_e32 v50, v47
	v_pk_fma_f32 v[44:45], v[16:17], v[50:51], v[44:45]
	s_nop 0
	v_add_f32_e32 v43, v43, v44
	v_add_f32_e32 v43, v43, v45
	v_min_f32_e32 v44, 0, v43
	v_mul_f32_e64 v43, |v43|, s82
	v_exp_f32_e32 v43, v43
	s_nop 0
	v_add_f32_e32 v43, 1.0, v43
	v_cmp_gt_f32_e32 vcc, s2, v43
	s_nop 1
	v_cndmask_b32_e64 v45, 0, 32, vcc
	v_ldexp_f32 v43, v43, v45
	v_log_f32_e32 v43, v43
	s_nop 0
	v_mul_f32_e32 v45, 0x3f317217, v43
	v_fma_f32 v45, v43, s85, -v45
	v_fmac_f32_e32 v45, 0x3377d1cf, v43
	v_fmac_f32_e32 v45, 0x3f317217, v43
	v_cmp_lt_f32_e64 s[42:43], |v43|, s83
	s_nop 1
	v_cndmask_b32_e64 v43, v43, v45, s[42:43]
	v_cndmask_b32_e32 v45, 0, v200, vcc
	v_sub_f32_e32 v43, v43, v45
	v_sub_f32_e32 v43, v44, v43
	ds_read_b128 v[44:47], v65 offset:384
	ds_read_b128 v[48:51], v65 offset:400
	v_fmamk_f32 v77, v43, 0x3d800000, v76
	s_waitcnt lgkmcnt(1)
	v_mov_b32_e32 v52, v44
	s_waitcnt lgkmcnt(0)
	v_mov_b32_e32 v53, v48
	v_mov_b32_e32 v48, v45
	v_pk_mul_f32 v[44:45], v[6:7], v[48:49]
	v_mov_b32_e32 v48, v46
	v_pk_fma_f32 v[44:45], v[4:5], v[52:53], v[44:45]
	v_mov_b32_e32 v49, v50
	v_pk_fma_f32 v[44:45], v[2:3], v[48:49], v[44:45]
	v_mov_b32_e32 v50, v47
	v_pk_fma_f32 v[44:45], v[8:9], v[50:51], v[44:45]
	s_nop 0
	v_add_f32_e32 v43, v42, v44
	v_add_f32_e32 v43, v43, v45
	ds_read_b128 v[44:47], v65 offset:416
	ds_read_b128 v[48:51], v65 offset:432
	s_waitcnt lgkmcnt(1)
	v_mov_b32_e32 v52, v44
	s_waitcnt lgkmcnt(0)
	v_mov_b32_e32 v53, v48
	v_mov_b32_e32 v48, v45
	v_pk_mul_f32 v[44:45], v[14:15], v[48:49]
	v_mov_b32_e32 v48, v46
	v_pk_fma_f32 v[44:45], v[12:13], v[52:53], v[44:45]
	v_mov_b32_e32 v49, v50
	v_pk_fma_f32 v[44:45], v[10:11], v[48:49], v[44:45]
	v_mov_b32_e32 v50, v47
	v_pk_fma_f32 v[44:45], v[16:17], v[50:51], v[44:45]
	s_nop 0
	v_add_f32_e32 v43, v43, v44
	v_add_f32_e32 v43, v43, v45
	v_min_f32_e32 v44, 0, v43
	v_mul_f32_e64 v43, |v43|, s82
	v_exp_f32_e32 v43, v43
	s_nop 0
	v_add_f32_e32 v43, 1.0, v43
	v_cmp_gt_f32_e32 vcc, s2, v43
	s_nop 1
	v_cndmask_b32_e64 v45, 0, 32, vcc
	v_ldexp_f32 v43, v43, v45
	v_log_f32_e32 v43, v43
	s_nop 0
	v_mul_f32_e32 v45, 0x3f317217, v43
	v_fma_f32 v45, v43, s85, -v45
	v_fmac_f32_e32 v45, 0x3377d1cf, v43
	v_fmac_f32_e32 v45, 0x3f317217, v43
	v_cmp_lt_f32_e64 s[42:43], |v43|, s83
	s_nop 1
	v_cndmask_b32_e64 v43, v43, v45, s[42:43]
	v_cndmask_b32_e32 v45, 0, v200, vcc
	v_sub_f32_e32 v43, v43, v45
	v_sub_f32_e32 v43, v44, v43
	ds_read_b128 v[44:47], v65 offset:448
	ds_read_b128 v[48:51], v65 offset:464
	v_fmamk_f32 v78, v43, 0x3d800000, v77
	s_waitcnt lgkmcnt(1)
	v_mov_b32_e32 v52, v44
	s_waitcnt lgkmcnt(0)
	v_mov_b32_e32 v53, v48
	v_mov_b32_e32 v48, v45
	v_pk_mul_f32 v[44:45], v[6:7], v[48:49]
	v_mov_b32_e32 v48, v46
	v_pk_fma_f32 v[44:45], v[4:5], v[52:53], v[44:45]
	v_mov_b32_e32 v49, v50
	v_pk_fma_f32 v[44:45], v[2:3], v[48:49], v[44:45]
	v_mov_b32_e32 v50, v47
	v_pk_fma_f32 v[44:45], v[8:9], v[50:51], v[44:45]
	s_nop 0
	v_add_f32_e32 v43, v42, v44
	v_add_f32_e32 v43, v43, v45
	ds_read_b128 v[44:47], v65 offset:480
	ds_read_b128 v[48:51], v65 offset:496
	s_waitcnt lgkmcnt(1)
	v_mov_b32_e32 v52, v44
	s_waitcnt lgkmcnt(0)
	v_mov_b32_e32 v53, v48
	v_mov_b32_e32 v48, v45
	v_pk_mul_f32 v[44:45], v[14:15], v[48:49]
	v_mov_b32_e32 v48, v46
	v_pk_fma_f32 v[44:45], v[12:13], v[52:53], v[44:45]
	v_mov_b32_e32 v49, v50
	v_pk_fma_f32 v[44:45], v[10:11], v[48:49], v[44:45]
	v_mov_b32_e32 v50, v47
	v_pk_fma_f32 v[44:45], v[16:17], v[50:51], v[44:45]
	s_nop 0
	v_add_f32_e32 v43, v43, v44
	v_add_f32_e32 v43, v43, v45
	v_min_f32_e32 v44, 0, v43
	v_mul_f32_e64 v43, |v43|, s82
	v_exp_f32_e32 v43, v43
	s_nop 0
	v_add_f32_e32 v43, 1.0, v43
	v_cmp_gt_f32_e32 vcc, s2, v43
	s_nop 1
	v_cndmask_b32_e64 v45, 0, 32, vcc
	v_ldexp_f32 v43, v43, v45
	v_log_f32_e32 v43, v43
	s_nop 0
	v_mul_f32_e32 v45, 0x3f317217, v43
	v_fma_f32 v45, v43, s85, -v45
	v_fmac_f32_e32 v45, 0x3377d1cf, v43
	v_fmac_f32_e32 v45, 0x3f317217, v43
	v_cmp_lt_f32_e64 s[42:43], |v43|, s83
	s_nop 1
	v_cndmask_b32_e64 v43, v43, v45, s[42:43]
	v_cndmask_b32_e32 v45, 0, v200, vcc
	v_sub_f32_e32 v43, v43, v45
	v_sub_f32_e32 v43, v44, v43
	ds_read_b128 v[44:47], v65 offset:512
	ds_read_b128 v[48:51], v65 offset:528
	v_fmamk_f32 v79, v43, 0x3d800000, v78
	s_waitcnt lgkmcnt(1)
	v_mov_b32_e32 v52, v44
	s_waitcnt lgkmcnt(0)
	v_mov_b32_e32 v53, v48
	v_mov_b32_e32 v48, v45
	v_pk_mul_f32 v[44:45], v[6:7], v[48:49]
	v_mov_b32_e32 v48, v46
	v_pk_fma_f32 v[44:45], v[4:5], v[52:53], v[44:45]
	v_mov_b32_e32 v49, v50
	v_pk_fma_f32 v[44:45], v[2:3], v[48:49], v[44:45]
	v_mov_b32_e32 v50, v47
	v_pk_fma_f32 v[44:45], v[8:9], v[50:51], v[44:45]
	s_nop 0
	v_add_f32_e32 v43, v42, v44
	v_add_f32_e32 v43, v43, v45
	ds_read_b128 v[44:47], v65 offset:544
	ds_read_b128 v[48:51], v65 offset:560
	s_waitcnt lgkmcnt(1)
	v_mov_b32_e32 v52, v44
	s_waitcnt lgkmcnt(0)
	v_mov_b32_e32 v53, v48
	v_mov_b32_e32 v48, v45
	v_pk_mul_f32 v[44:45], v[14:15], v[48:49]
	v_mov_b32_e32 v48, v46
	v_pk_fma_f32 v[44:45], v[12:13], v[52:53], v[44:45]
	v_mov_b32_e32 v49, v50
	v_pk_fma_f32 v[44:45], v[10:11], v[48:49], v[44:45]
	v_mov_b32_e32 v50, v47
	v_pk_fma_f32 v[44:45], v[16:17], v[50:51], v[44:45]
	s_nop 0
	v_add_f32_e32 v43, v43, v44
	v_add_f32_e32 v43, v43, v45
	v_min_f32_e32 v44, 0, v43
	v_mul_f32_e64 v43, |v43|, s82
	v_exp_f32_e32 v43, v43
	s_nop 0
	v_add_f32_e32 v43, 1.0, v43
	v_cmp_gt_f32_e32 vcc, s2, v43
	s_nop 1
	v_cndmask_b32_e64 v45, 0, 32, vcc
	v_ldexp_f32 v43, v43, v45
	v_log_f32_e32 v43, v43
	s_nop 0
	v_mul_f32_e32 v45, 0x3f317217, v43
	v_fma_f32 v45, v43, s85, -v45
	v_fmac_f32_e32 v45, 0x3377d1cf, v43
	v_fmac_f32_e32 v45, 0x3f317217, v43
	v_cmp_lt_f32_e64 s[42:43], |v43|, s83
	s_nop 1
	v_cndmask_b32_e64 v43, v43, v45, s[42:43]
	v_cndmask_b32_e32 v45, 0, v200, vcc
	v_sub_f32_e32 v43, v43, v45
	v_sub_f32_e32 v43, v44, v43
	ds_read_b128 v[44:47], v65 offset:576
	ds_read_b128 v[48:51], v65 offset:592
	v_fmamk_f32 v80, v43, 0x3d800000, v79
	s_waitcnt lgkmcnt(1)
	v_mov_b32_e32 v52, v44
	s_waitcnt lgkmcnt(0)
	v_mov_b32_e32 v53, v48
	v_mov_b32_e32 v48, v45
	v_pk_mul_f32 v[44:45], v[6:7], v[48:49]
	v_mov_b32_e32 v48, v46
	v_pk_fma_f32 v[44:45], v[4:5], v[52:53], v[44:45]
	v_mov_b32_e32 v49, v50
	v_pk_fma_f32 v[44:45], v[2:3], v[48:49], v[44:45]
	v_mov_b32_e32 v50, v47
	v_pk_fma_f32 v[44:45], v[8:9], v[50:51], v[44:45]
	s_nop 0
	v_add_f32_e32 v43, v42, v44
	v_add_f32_e32 v43, v43, v45
	ds_read_b128 v[44:47], v65 offset:608
	ds_read_b128 v[48:51], v65 offset:624
	s_waitcnt lgkmcnt(1)
	v_mov_b32_e32 v52, v44
	s_waitcnt lgkmcnt(0)
	v_mov_b32_e32 v53, v48
	v_mov_b32_e32 v48, v45
	v_pk_mul_f32 v[44:45], v[14:15], v[48:49]
	v_mov_b32_e32 v48, v46
	v_pk_fma_f32 v[44:45], v[12:13], v[52:53], v[44:45]
	v_mov_b32_e32 v49, v50
	v_pk_fma_f32 v[44:45], v[10:11], v[48:49], v[44:45]
	v_mov_b32_e32 v50, v47
	v_pk_fma_f32 v[44:45], v[16:17], v[50:51], v[44:45]
	s_nop 0
	v_add_f32_e32 v43, v43, v44
	v_add_f32_e32 v43, v43, v45
	v_min_f32_e32 v44, 0, v43
	v_mul_f32_e64 v43, |v43|, s82
	v_exp_f32_e32 v43, v43
	s_nop 0
	v_add_f32_e32 v43, 1.0, v43
	v_cmp_gt_f32_e32 vcc, s2, v43
	s_nop 1
	v_cndmask_b32_e64 v45, 0, 32, vcc
	v_ldexp_f32 v43, v43, v45
	v_log_f32_e32 v43, v43
	s_nop 0
	v_mul_f32_e32 v45, 0x3f317217, v43
	v_fma_f32 v45, v43, s85, -v45
	v_fmac_f32_e32 v45, 0x3377d1cf, v43
	v_fmac_f32_e32 v45, 0x3f317217, v43
	v_cmp_lt_f32_e64 s[42:43], |v43|, s83
	s_nop 1
	v_cndmask_b32_e64 v43, v43, v45, s[42:43]
	v_cndmask_b32_e32 v45, 0, v200, vcc
	v_sub_f32_e32 v43, v43, v45
	v_sub_f32_e32 v43, v44, v43
	ds_read_b128 v[44:47], v65 offset:640
	ds_read_b128 v[48:51], v65 offset:656
	v_fmamk_f32 v81, v43, 0x3d800000, v80
	s_waitcnt lgkmcnt(1)
	v_mov_b32_e32 v52, v44
	s_waitcnt lgkmcnt(0)
	v_mov_b32_e32 v53, v48
	v_mov_b32_e32 v48, v45
	v_pk_mul_f32 v[44:45], v[6:7], v[48:49]
	v_mov_b32_e32 v48, v46
	v_pk_fma_f32 v[44:45], v[4:5], v[52:53], v[44:45]
	v_mov_b32_e32 v49, v50
	v_pk_fma_f32 v[44:45], v[2:3], v[48:49], v[44:45]
	v_mov_b32_e32 v50, v47
	v_pk_fma_f32 v[44:45], v[8:9], v[50:51], v[44:45]
	s_nop 0
	v_add_f32_e32 v43, v42, v44
	v_add_f32_e32 v43, v43, v45
	ds_read_b128 v[44:47], v65 offset:672
	ds_read_b128 v[48:51], v65 offset:688
	s_waitcnt lgkmcnt(1)
	v_mov_b32_e32 v52, v44
	s_waitcnt lgkmcnt(0)
	v_mov_b32_e32 v53, v48
	v_mov_b32_e32 v48, v45
	v_pk_mul_f32 v[44:45], v[14:15], v[48:49]
	v_mov_b32_e32 v48, v46
	v_pk_fma_f32 v[44:45], v[12:13], v[52:53], v[44:45]
	v_mov_b32_e32 v49, v50
	v_pk_fma_f32 v[44:45], v[10:11], v[48:49], v[44:45]
	v_mov_b32_e32 v50, v47
	v_pk_fma_f32 v[44:45], v[16:17], v[50:51], v[44:45]
	s_nop 0
	v_add_f32_e32 v43, v43, v44
	v_add_f32_e32 v43, v43, v45
	v_min_f32_e32 v44, 0, v43
	v_mul_f32_e64 v43, |v43|, s82
	v_exp_f32_e32 v43, v43
	s_nop 0
	v_add_f32_e32 v43, 1.0, v43
	v_cmp_gt_f32_e32 vcc, s2, v43
	s_nop 1
	v_cndmask_b32_e64 v45, 0, 32, vcc
	v_ldexp_f32 v43, v43, v45
	v_log_f32_e32 v43, v43
	s_nop 0
	v_mul_f32_e32 v45, 0x3f317217, v43
	v_fma_f32 v45, v43, s85, -v45
	v_fmac_f32_e32 v45, 0x3377d1cf, v43
	v_fmac_f32_e32 v45, 0x3f317217, v43
	v_cmp_lt_f32_e64 s[42:43], |v43|, s83
	s_nop 1
	v_cndmask_b32_e64 v43, v43, v45, s[42:43]
	v_cndmask_b32_e32 v45, 0, v200, vcc
	v_sub_f32_e32 v43, v43, v45
	v_sub_f32_e32 v43, v44, v43
	ds_read_b128 v[44:47], v65 offset:704
	ds_read_b128 v[48:51], v65 offset:720
	v_fmamk_f32 v82, v43, 0x3d800000, v81
	s_waitcnt lgkmcnt(1)
	v_mov_b32_e32 v52, v44
	s_waitcnt lgkmcnt(0)
	v_mov_b32_e32 v53, v48
	v_mov_b32_e32 v48, v45
	v_pk_mul_f32 v[44:45], v[6:7], v[48:49]
	v_mov_b32_e32 v48, v46
	v_pk_fma_f32 v[44:45], v[4:5], v[52:53], v[44:45]
	v_mov_b32_e32 v49, v50
	v_pk_fma_f32 v[44:45], v[2:3], v[48:49], v[44:45]
	v_mov_b32_e32 v50, v47
	v_pk_fma_f32 v[44:45], v[8:9], v[50:51], v[44:45]
	s_nop 0
	v_add_f32_e32 v43, v42, v44
	v_add_f32_e32 v43, v43, v45
	ds_read_b128 v[44:47], v65 offset:736
	ds_read_b128 v[48:51], v65 offset:752
	s_waitcnt lgkmcnt(1)
	v_mov_b32_e32 v52, v44
	s_waitcnt lgkmcnt(0)
	v_mov_b32_e32 v53, v48
	v_mov_b32_e32 v48, v45
	v_pk_mul_f32 v[44:45], v[14:15], v[48:49]
	v_mov_b32_e32 v48, v46
	v_pk_fma_f32 v[44:45], v[12:13], v[52:53], v[44:45]
	v_mov_b32_e32 v49, v50
	v_pk_fma_f32 v[44:45], v[10:11], v[48:49], v[44:45]
	v_mov_b32_e32 v50, v47
	v_pk_fma_f32 v[44:45], v[16:17], v[50:51], v[44:45]
	s_nop 0
	v_add_f32_e32 v43, v43, v44
	v_add_f32_e32 v43, v43, v45
	v_min_f32_e32 v44, 0, v43
	v_mul_f32_e64 v43, |v43|, s82
	v_exp_f32_e32 v43, v43
	s_nop 0
	v_add_f32_e32 v43, 1.0, v43
	v_cmp_gt_f32_e32 vcc, s2, v43
	s_nop 1
	v_cndmask_b32_e64 v45, 0, 32, vcc
	v_ldexp_f32 v43, v43, v45
	v_log_f32_e32 v43, v43
	s_nop 0
	v_mul_f32_e32 v45, 0x3f317217, v43
	v_fma_f32 v45, v43, s85, -v45
	v_fmac_f32_e32 v45, 0x3377d1cf, v43
	v_fmac_f32_e32 v45, 0x3f317217, v43
	v_cmp_lt_f32_e64 s[42:43], |v43|, s83
	s_nop 1
	v_cndmask_b32_e64 v43, v43, v45, s[42:43]
	v_cndmask_b32_e32 v45, 0, v200, vcc
	v_sub_f32_e32 v43, v43, v45
	v_sub_f32_e32 v43, v44, v43
	ds_read_b128 v[44:47], v65 offset:768
	ds_read_b128 v[48:51], v65 offset:784
	v_fmamk_f32 v83, v43, 0x3d800000, v82
	s_waitcnt lgkmcnt(1)
	v_mov_b32_e32 v52, v44
	s_waitcnt lgkmcnt(0)
	v_mov_b32_e32 v53, v48
	v_mov_b32_e32 v48, v45
	v_pk_mul_f32 v[44:45], v[6:7], v[48:49]
	v_mov_b32_e32 v48, v46
	v_pk_fma_f32 v[44:45], v[4:5], v[52:53], v[44:45]
	v_mov_b32_e32 v49, v50
	v_pk_fma_f32 v[44:45], v[2:3], v[48:49], v[44:45]
	v_mov_b32_e32 v50, v47
	v_pk_fma_f32 v[44:45], v[8:9], v[50:51], v[44:45]
	s_nop 0
	v_add_f32_e32 v43, v42, v44
	v_add_f32_e32 v43, v43, v45
	ds_read_b128 v[44:47], v65 offset:800
	ds_read_b128 v[48:51], v65 offset:816
	s_waitcnt lgkmcnt(1)
	v_mov_b32_e32 v52, v44
	s_waitcnt lgkmcnt(0)
	v_mov_b32_e32 v53, v48
	v_mov_b32_e32 v48, v45
	v_pk_mul_f32 v[44:45], v[14:15], v[48:49]
	v_mov_b32_e32 v48, v46
	v_pk_fma_f32 v[44:45], v[12:13], v[52:53], v[44:45]
	v_mov_b32_e32 v49, v50
	v_pk_fma_f32 v[44:45], v[10:11], v[48:49], v[44:45]
	v_mov_b32_e32 v50, v47
	v_pk_fma_f32 v[44:45], v[16:17], v[50:51], v[44:45]
	s_nop 0
	v_add_f32_e32 v43, v43, v44
	v_add_f32_e32 v43, v43, v45
	v_min_f32_e32 v44, 0, v43
	v_mul_f32_e64 v43, |v43|, s82
	v_exp_f32_e32 v43, v43
	s_nop 0
	v_add_f32_e32 v43, 1.0, v43
	v_cmp_gt_f32_e32 vcc, s2, v43
	s_nop 1
	v_cndmask_b32_e64 v45, 0, 32, vcc
	v_ldexp_f32 v43, v43, v45
	v_log_f32_e32 v43, v43
	s_nop 0
	v_mul_f32_e32 v45, 0x3f317217, v43
	v_fma_f32 v45, v43, s85, -v45
	v_fmac_f32_e32 v45, 0x3377d1cf, v43
	v_fmac_f32_e32 v45, 0x3f317217, v43
	v_cmp_lt_f32_e64 s[42:43], |v43|, s83
	s_nop 1
	v_cndmask_b32_e64 v43, v43, v45, s[42:43]
	v_cndmask_b32_e32 v45, 0, v200, vcc
	v_sub_f32_e32 v43, v43, v45
	v_sub_f32_e32 v43, v44, v43
	ds_read_b128 v[44:47], v65 offset:832
	ds_read_b128 v[48:51], v65 offset:848
	v_fmamk_f32 v84, v43, 0x3d800000, v83
	s_waitcnt lgkmcnt(1)
	v_mov_b32_e32 v52, v44
	s_waitcnt lgkmcnt(0)
	v_mov_b32_e32 v53, v48
	v_mov_b32_e32 v48, v45
	v_pk_mul_f32 v[44:45], v[6:7], v[48:49]
	v_mov_b32_e32 v48, v46
	v_pk_fma_f32 v[44:45], v[4:5], v[52:53], v[44:45]
	v_mov_b32_e32 v49, v50
	v_pk_fma_f32 v[44:45], v[2:3], v[48:49], v[44:45]
	v_mov_b32_e32 v50, v47
	v_pk_fma_f32 v[44:45], v[8:9], v[50:51], v[44:45]
	s_nop 0
	v_add_f32_e32 v43, v42, v44
	v_add_f32_e32 v43, v43, v45
	ds_read_b128 v[44:47], v65 offset:864
	ds_read_b128 v[48:51], v65 offset:880
	s_waitcnt lgkmcnt(1)
	v_mov_b32_e32 v52, v44
	s_waitcnt lgkmcnt(0)
	v_mov_b32_e32 v53, v48
	v_mov_b32_e32 v48, v45
	v_pk_mul_f32 v[44:45], v[14:15], v[48:49]
	v_mov_b32_e32 v48, v46
	v_pk_fma_f32 v[44:45], v[12:13], v[52:53], v[44:45]
	v_mov_b32_e32 v49, v50
	v_pk_fma_f32 v[44:45], v[10:11], v[48:49], v[44:45]
	v_mov_b32_e32 v50, v47
	v_pk_fma_f32 v[44:45], v[16:17], v[50:51], v[44:45]
	s_nop 0
	v_add_f32_e32 v43, v43, v44
	v_add_f32_e32 v43, v43, v45
	v_min_f32_e32 v44, 0, v43
	v_mul_f32_e64 v43, |v43|, s82
	v_exp_f32_e32 v43, v43
	s_nop 0
	v_add_f32_e32 v43, 1.0, v43
	v_cmp_gt_f32_e32 vcc, s2, v43
	s_nop 1
	v_cndmask_b32_e64 v45, 0, 32, vcc
	v_ldexp_f32 v43, v43, v45
	v_log_f32_e32 v43, v43
	s_nop 0
	v_mul_f32_e32 v45, 0x3f317217, v43
	v_fma_f32 v45, v43, s85, -v45
	v_fmac_f32_e32 v45, 0x3377d1cf, v43
	v_fmac_f32_e32 v45, 0x3f317217, v43
	v_cmp_lt_f32_e64 s[42:43], |v43|, s83
	s_nop 1
	v_cndmask_b32_e64 v43, v43, v45, s[42:43]
	v_cndmask_b32_e32 v45, 0, v200, vcc
	v_sub_f32_e32 v43, v43, v45
	v_sub_f32_e32 v43, v44, v43
	ds_read_b128 v[44:47], v65 offset:896
	ds_read_b128 v[48:51], v65 offset:912
	v_fmamk_f32 v85, v43, 0x3d800000, v84
	s_waitcnt lgkmcnt(1)
	v_mov_b32_e32 v52, v44
	s_waitcnt lgkmcnt(0)
	v_mov_b32_e32 v53, v48
	v_mov_b32_e32 v48, v45
	v_pk_mul_f32 v[44:45], v[6:7], v[48:49]
	v_mov_b32_e32 v48, v46
	v_pk_fma_f32 v[44:45], v[4:5], v[52:53], v[44:45]
	v_mov_b32_e32 v49, v50
	v_pk_fma_f32 v[44:45], v[2:3], v[48:49], v[44:45]
	v_mov_b32_e32 v50, v47
	v_pk_fma_f32 v[44:45], v[8:9], v[50:51], v[44:45]
	s_nop 0
	v_add_f32_e32 v43, v42, v44
	v_add_f32_e32 v43, v43, v45
	ds_read_b128 v[44:47], v65 offset:928
	ds_read_b128 v[48:51], v65 offset:944
	s_waitcnt lgkmcnt(1)
	v_mov_b32_e32 v52, v44
	s_waitcnt lgkmcnt(0)
	v_mov_b32_e32 v53, v48
	v_mov_b32_e32 v48, v45
	v_pk_mul_f32 v[44:45], v[14:15], v[48:49]
	v_mov_b32_e32 v48, v46
	v_pk_fma_f32 v[44:45], v[12:13], v[52:53], v[44:45]
	v_mov_b32_e32 v49, v50
	v_pk_fma_f32 v[44:45], v[10:11], v[48:49], v[44:45]
	v_mov_b32_e32 v50, v47
	v_pk_fma_f32 v[44:45], v[16:17], v[50:51], v[44:45]
	s_nop 0
	v_add_f32_e32 v43, v43, v44
	v_add_f32_e32 v43, v43, v45
	v_min_f32_e32 v44, 0, v43
	v_mul_f32_e64 v43, |v43|, s82
	v_exp_f32_e32 v43, v43
	s_nop 0
	v_add_f32_e32 v43, 1.0, v43
	v_cmp_gt_f32_e32 vcc, s2, v43
	s_nop 1
	v_cndmask_b32_e64 v45, 0, 32, vcc
	v_ldexp_f32 v43, v43, v45
	v_log_f32_e32 v43, v43
	s_nop 0
	v_mul_f32_e32 v45, 0x3f317217, v43
	v_fma_f32 v45, v43, s85, -v45
	v_fmac_f32_e32 v45, 0x3377d1cf, v43
	v_fmac_f32_e32 v45, 0x3f317217, v43
	v_cmp_lt_f32_e64 s[42:43], |v43|, s83
	s_nop 1
	v_cndmask_b32_e64 v43, v43, v45, s[42:43]
	v_cndmask_b32_e32 v45, 0, v200, vcc
	v_sub_f32_e32 v43, v43, v45
	v_sub_f32_e32 v43, v44, v43
	ds_read_b128 v[44:47], v65 offset:960
	ds_read_b128 v[48:51], v65 offset:976
	v_fmamk_f32 v86, v43, 0x3d800000, v85
	s_waitcnt lgkmcnt(1)
	v_mov_b32_e32 v52, v44
	s_waitcnt lgkmcnt(0)
	v_mov_b32_e32 v53, v48
	v_mov_b32_e32 v48, v45
	v_pk_mul_f32 v[6:7], v[6:7], v[48:49]
	s_nop 0
	v_pk_fma_f32 v[4:5], v[4:5], v[52:53], v[6:7]
	v_mov_b32_e32 v6, v46
	v_mov_b32_e32 v7, v50
	v_pk_fma_f32 v[2:3], v[2:3], v[6:7], v[4:5]
	v_mov_b32_e32 v50, v47
	v_pk_fma_f32 v[2:3], v[8:9], v[50:51], v[2:3]
	s_nop 0
	v_add_f32_e32 v2, v42, v2
	v_add_f32_e32 v44, v2, v3
	ds_read_b128 v[2:5], v65 offset:992
	ds_read_b128 v[6:9], v65 offset:1008
	s_waitcnt lgkmcnt(1)
	v_mov_b32_e32 v42, v2
	s_waitcnt lgkmcnt(0)
	v_mov_b32_e32 v43, v6
	v_mov_b32_e32 v6, v3
	v_pk_mul_f32 v[2:3], v[14:15], v[6:7]
	v_mov_b32_e32 v6, v4
	v_pk_fma_f32 v[2:3], v[12:13], v[42:43], v[2:3]
	v_mov_b32_e32 v7, v8
	v_pk_fma_f32 v[2:3], v[10:11], v[6:7], v[2:3]
	v_mov_b32_e32 v8, v5
	v_pk_fma_f32 v[2:3], v[16:17], v[8:9], v[2:3]
	s_nop 0
	v_add_f32_e32 v2, v44, v2
	v_add_f32_e32 v2, v2, v3
	v_min_f32_e32 v3, 0, v2
	v_mul_f32_e64 v2, |v2|, s82
	v_exp_f32_e32 v2, v2
	s_nop 0
	v_add_f32_e32 v2, 1.0, v2
	v_cmp_gt_f32_e32 vcc, s2, v2
	s_nop 1
	v_cndmask_b32_e64 v4, 0, 32, vcc
	v_ldexp_f32 v2, v2, v4
	v_log_f32_e32 v2, v2
	s_nop 0
	v_mul_f32_e32 v4, 0x3f317217, v2
	v_fma_f32 v4, v2, s85, -v4
	v_fmac_f32_e32 v4, 0x3377d1cf, v2
	v_fmac_f32_e32 v4, 0x3f317217, v2
	v_cmp_lt_f32_e64 s[42:43], |v2|, s83
	s_nop 1
	v_cndmask_b32_e64 v2, v2, v4, s[42:43]
	v_cndmask_b32_e32 v4, 0, v200, vcc
	v_sub_f32_e32 v2, v2, v4
	v_sub_f32_e32 v2, v3, v2
	v_fmamk_f32 v87, v2, 0x3d800000, v86
	ds_write_b32 v28, v87 offset:4096
